# retention chunk-state recurrences keep four steps of loads in flight
# baseline (speedup 1.0000x reference)
.LBB0_975:
	s_waitcnt vmcnt(1)
	v_mul_f32_e32 v18, 0x3fb8aa3b, v18
	v_exp_f32_e32 v106, v18
	s_and_b32 s40, s6, s37
	s_cmp_eq_u32 s40, 0
	s_cselect_b64 s[6:7], -1, 0
	v_mul_f32_e32 v18, 0xc3000000, v106
	v_mul_f32_e32 v18, 0x3fb8aa3b, v18
	v_exp_f32_e32 v26, v18
	s_lshl_b32 s0, s38, 3
	s_lshl_b32 s9, s39, 1
	s_and_b64 vcc, exec, s[6:7]
	s_cbranch_vccnz .LBB0_978
	s_add_i32 s12, s0, s9
	s_ashr_i32 s13, s12, 31
	s_lshl_b64 s[12:13], s[12:13], 18
	v_mov_b32_e32 v27, v26
	s_lshl_b32 s14, s40, 14
	v_lshl_add_u64 v[18:19], v[88:89], 0, s[12:13]
	s_mov_b64 s[12:13], 0
	s_add_u32 s70, s14, 0xffffc000
	s_mov_b32 s72, 0
	s_mov_b32 s75, 0
	s_min_u32 s74, s72, s70
	s_add_u32 s72, s72, 0x4000
	v_lshl_add_u64 v[240:241], v[18:19], 0, s[74:75]
	global_load_dwordx4 v[108:111], v[240:241], off
	global_load_dwordx4 v[112:115], v[240:241], off offset:16
	global_load_dwordx4 v[116:119], v[240:241], off offset:32
	global_load_dwordx4 v[120:123], v[240:241], off offset:48
	s_min_u32 s74, s72, s70
	s_add_u32 s72, s72, 0x4000
	v_lshl_add_u64 v[240:241], v[18:19], 0, s[74:75]
	global_load_dwordx4 v[124:127], v[240:241], off
	global_load_dwordx4 v[128:131], v[240:241], off offset:16
	global_load_dwordx4 v[132:135], v[240:241], off offset:32
	global_load_dwordx4 v[136:139], v[240:241], off offset:48
	s_min_u32 s74, s72, s70
	s_add_u32 s72, s72, 0x4000
	v_lshl_add_u64 v[240:241], v[18:19], 0, s[74:75]
	global_load_dwordx4 v[160:163], v[240:241], off
	global_load_dwordx4 v[164:167], v[240:241], off offset:16
	global_load_dwordx4 v[168:171], v[240:241], off offset:32
	global_load_dwordx4 v[172:175], v[240:241], off offset:48
.LBB0_977:
	s_min_u32 s74, s72, s70
	s_add_u32 s72, s72, 0x4000
	v_lshl_add_u64 v[240:241], v[18:19], 0, s[74:75]
	global_load_dwordx4 v[216:219], v[240:241], off
	global_load_dwordx4 v[220:223], v[240:241], off offset:16
	global_load_dwordx4 v[224:227], v[240:241], off offset:32
	global_load_dwordx4 v[228:231], v[240:241], off offset:48
	s_waitcnt vmcnt(12)
	v_pk_fma_f32 v[2:3], v[26:27], v[2:3], v[108:109]
	v_pk_fma_f32 v[4:5], v[26:27], v[4:5], v[110:111]
	v_pk_fma_f32 v[6:7], v[26:27], v[6:7], v[112:113]
	v_pk_fma_f32 v[8:9], v[26:27], v[8:9], v[114:115]
	v_pk_fma_f32 v[10:11], v[26:27], v[10:11], v[116:117]
	v_pk_fma_f32 v[12:13], v[26:27], v[12:13], v[118:119]
	v_pk_fma_f32 v[14:15], v[26:27], v[14:15], v[120:121]
	v_pk_fma_f32 v[16:17], v[26:27], v[16:17], v[122:123]
	s_add_u32 s12, s12, 0x4000
	s_addc_u32 s13, s13, 0
	s_cmp_eq_u32 s14, s12
	s_cbranch_scc1 .Lp2c_fdone
	s_min_u32 s74, s72, s70
	s_add_u32 s72, s72, 0x4000
	v_lshl_add_u64 v[240:241], v[18:19], 0, s[74:75]
	global_load_dwordx4 v[108:111], v[240:241], off
	global_load_dwordx4 v[112:115], v[240:241], off offset:16
	global_load_dwordx4 v[116:119], v[240:241], off offset:32
	global_load_dwordx4 v[120:123], v[240:241], off offset:48
	s_waitcnt vmcnt(12)
	v_pk_fma_f32 v[2:3], v[26:27], v[2:3], v[124:125]
	v_pk_fma_f32 v[4:5], v[26:27], v[4:5], v[126:127]
	v_pk_fma_f32 v[6:7], v[26:27], v[6:7], v[128:129]
	v_pk_fma_f32 v[8:9], v[26:27], v[8:9], v[130:131]
	v_pk_fma_f32 v[10:11], v[26:27], v[10:11], v[132:133]
	v_pk_fma_f32 v[12:13], v[26:27], v[12:13], v[134:135]
	v_pk_fma_f32 v[14:15], v[26:27], v[14:15], v[136:137]
	v_pk_fma_f32 v[16:17], v[26:27], v[16:17], v[138:139]
	s_add_u32 s12, s12, 0x4000
	s_addc_u32 s13, s13, 0
	s_cmp_eq_u32 s14, s12
	s_cbranch_scc1 .Lp2c_fdone
	s_min_u32 s74, s72, s70
	s_add_u32 s72, s72, 0x4000
	v_lshl_add_u64 v[240:241], v[18:19], 0, s[74:75]
	global_load_dwordx4 v[124:127], v[240:241], off
	global_load_dwordx4 v[128:131], v[240:241], off offset:16
	global_load_dwordx4 v[132:135], v[240:241], off offset:32
	global_load_dwordx4 v[136:139], v[240:241], off offset:48
	s_waitcnt vmcnt(12)
	v_pk_fma_f32 v[2:3], v[26:27], v[2:3], v[160:161]
	v_pk_fma_f32 v[4:5], v[26:27], v[4:5], v[162:163]
	v_pk_fma_f32 v[6:7], v[26:27], v[6:7], v[164:165]
	v_pk_fma_f32 v[8:9], v[26:27], v[8:9], v[166:167]
	v_pk_fma_f32 v[10:11], v[26:27], v[10:11], v[168:169]
	v_pk_fma_f32 v[12:13], v[26:27], v[12:13], v[170:171]
	v_pk_fma_f32 v[14:15], v[26:27], v[14:15], v[172:173]
	v_pk_fma_f32 v[16:17], v[26:27], v[16:17], v[174:175]
	s_add_u32 s12, s12, 0x4000
	s_addc_u32 s13, s13, 0
	s_cmp_eq_u32 s14, s12
	s_cbranch_scc1 .Lp2c_fdone
	s_min_u32 s74, s72, s70
	s_add_u32 s72, s72, 0x4000
	v_lshl_add_u64 v[240:241], v[18:19], 0, s[74:75]
	global_load_dwordx4 v[160:163], v[240:241], off
	global_load_dwordx4 v[164:167], v[240:241], off offset:16
	global_load_dwordx4 v[168:171], v[240:241], off offset:32
	global_load_dwordx4 v[172:175], v[240:241], off offset:48
	s_waitcnt vmcnt(12)
	v_pk_fma_f32 v[2:3], v[26:27], v[2:3], v[216:217]
	v_pk_fma_f32 v[4:5], v[26:27], v[4:5], v[218:219]
	v_pk_fma_f32 v[6:7], v[26:27], v[6:7], v[220:221]
	v_pk_fma_f32 v[8:9], v[26:27], v[8:9], v[222:223]
	v_pk_fma_f32 v[10:11], v[26:27], v[10:11], v[224:225]
	v_pk_fma_f32 v[12:13], v[26:27], v[12:13], v[226:227]
	v_pk_fma_f32 v[14:15], v[26:27], v[14:15], v[228:229]
	v_pk_fma_f32 v[16:17], v[26:27], v[16:17], v[230:231]
	s_add_u32 s12, s12, 0x4000
	s_addc_u32 s13, s13, 0
	s_cmp_eq_u32 s14, s12
	s_cbranch_scc0 .LBB0_977
.Lp2c_fdone:
.LBB0_978:
	s_lshl_b32 s13, s39, 12
	s_or_b32 s12, s0, s9
	s_lshl_b32 s0, s13, 2
	v_cvt_pk_bf16_f32 v2, v2, s0
	ds_write_b16 v105, v2 offset:35840
	v_cvt_pk_bf16_f32 v2, v3, s0
	ds_write_b16 v105, v2 offset:35984
	v_cvt_pk_bf16_f32 v2, v4, s0
	ds_write_b16 v105, v2 offset:36128
	v_cvt_pk_bf16_f32 v2, v5, s0
	ds_write_b16 v105, v2 offset:36272
	v_cvt_pk_bf16_f32 v2, v6, s0
	s_waitcnt vmcnt(0)
	v_mul_f32_e32 v18, 0x3fb8aa3b, v20
	ds_write_b16 v105, v2 offset:36416
	v_cvt_pk_bf16_f32 v2, v7, s0
	v_exp_f32_e32 v107, v18
	ds_write_b16 v105, v2 offset:36560
	v_cvt_pk_bf16_f32 v2, v8, s0
	ds_write_b16 v105, v2 offset:36704
	v_cvt_pk_bf16_f32 v2, v9, s0
	ds_write_b16 v105, v2 offset:36848
	v_cvt_pk_bf16_f32 v2, v10, s0
	ds_write_b16 v105, v2 offset:36992
	v_cvt_pk_bf16_f32 v2, v11, s0
	v_mul_f32_e32 v18, 0xc3000000, v107
	ds_write_b16 v105, v2 offset:37136
	v_cvt_pk_bf16_f32 v2, v12, s0
	v_mul_f32_e32 v18, 0x3fb8aa3b, v18
	ds_write_b16 v105, v2 offset:37280
	v_cvt_pk_bf16_f32 v2, v13, s0
	v_exp_f32_e32 v18, v18
	ds_write_b16 v105, v2 offset:37424
	v_cvt_pk_bf16_f32 v2, v14, s0
	ds_write_b16 v105, v2 offset:37568
	v_cvt_pk_bf16_f32 v2, v15, s0
	s_and_b64 s[14:15], s[6:7], s[4:5]
	ds_write_b16 v105, v2 offset:37712
	v_cvt_pk_bf16_f32 v2, v16, s0
	s_or_b32 s6, s42, s35
	v_lshl_add_u64 v[20:21], v[84:85], 0, s[0:1]
	ds_write_b16 v105, v2 offset:37856
	v_cvt_pk_bf16_f32 v2, v17, s0
	s_and_b64 vcc, exec, s[14:15]
	v_lshlrev_b32_e32 v24, 2, v66
	ds_write_b16 v105, v2 offset:38000
	s_cbranch_vccz .LBB0_980
	s_ashr_i32 s13, s12, 31
	v_readlane_b32 s44, v247, 49
	s_lshl_b64 s[42:43], s[12:13], 18
	v_readlane_b32 s54, v247, 59
	v_lshl_add_u64 v[2:3], v[82:83], 0, s[42:43]
	v_readlane_b32 s55, v247, 60
	s_add_u32 s42, s54, s42
	s_addc_u32 s43, s55, s43
	v_lshl_add_u64 v[4:5], v[68:69], 2, s[42:43]
	v_mov_b32_e32 v25, v1
	v_lshl_add_u64 v[4:5], v[4:5], 0, v[24:25]
	v_add_co_u32_e32 v6, vcc, s60, v4
	s_ashr_i32 s7, s6, 31
	s_nop 0
	v_addc_co_u32_e32 v7, vcc, 0, v5, vcc
	global_load_dword v8, v[2:3], off
	global_load_dword v9, v[6:7], off
	s_lshl_b64 s[42:43], s[6:7], 16
	v_lshl_add_u64 v[6:7], v[20:21], 0, s[42:43]
	s_mov_b64 s[42:43], 0x4000
	v_lshl_add_u64 v[4:5], v[4:5], 0, s[42:43]
	v_readlane_b32 s45, v247, 50
	v_readlane_b32 s46, v247, 51
	v_readlane_b32 s47, v247, 52
	v_readlane_b32 s48, v247, 53
	v_readlane_b32 s49, v247, 54
	v_readlane_b32 s50, v247, 55
	v_readlane_b32 s51, v247, 56
	v_readlane_b32 s52, v247, 57
	v_readlane_b32 s53, v247, 58
	v_readlane_b32 s56, v247, 61
	v_readlane_b32 s57, v247, 62
	v_readlane_b32 s58, v247, 63
	v_readlane_b32 s59, v246, 0
	s_waitcnt vmcnt(0)
	v_fmac_f32_e32 v9, v26, v8
	global_store_dword v[6:7], v9, off
	global_load_dword v8, v[2:3], off offset:4
	s_nop 0
	global_load_dword v9, v[4:5], off offset:4
	s_waitcnt vmcnt(0)
	v_fmac_f32_e32 v9, v26, v8
	global_store_dword v[6:7], v9, off offset:4
	global_load_dword v8, v[2:3], off offset:8
	s_nop 0
	global_load_dword v9, v[4:5], off offset:8
	s_waitcnt vmcnt(0)
	v_fmac_f32_e32 v9, v26, v8
	global_store_dword v[6:7], v9, off offset:8
	global_load_dword v8, v[2:3], off offset:12
	s_nop 0
	global_load_dword v9, v[4:5], off offset:12
	s_waitcnt vmcnt(0)
	v_fmac_f32_e32 v9, v26, v8
	global_store_dword v[6:7], v9, off offset:12
	global_load_dword v8, v[2:3], off offset:16
	s_nop 0
	global_load_dword v9, v[4:5], off offset:16
	s_waitcnt vmcnt(0)
	v_fmac_f32_e32 v9, v26, v8
	global_store_dword v[6:7], v9, off offset:16
	global_load_dword v8, v[2:3], off offset:20
	s_nop 0
	global_load_dword v9, v[4:5], off offset:20
	s_waitcnt vmcnt(0)
	v_fmac_f32_e32 v9, v26, v8
	global_store_dword v[6:7], v9, off offset:20
	global_load_dword v8, v[2:3], off offset:24
	s_nop 0
	global_load_dword v9, v[4:5], off offset:24
	s_waitcnt vmcnt(0)
	v_fmac_f32_e32 v9, v26, v8
	global_store_dword v[6:7], v9, off offset:24
	global_load_dword v8, v[2:3], off offset:28
	s_nop 0
	global_load_dword v9, v[4:5], off offset:28
	s_waitcnt vmcnt(0)
	v_fmac_f32_e32 v9, v26, v8
	global_store_dword v[6:7], v9, off offset:28
	global_load_dword v8, v[2:3], off offset:32
	s_nop 0
	global_load_dword v9, v[4:5], off offset:32
	s_waitcnt vmcnt(0)
	v_fmac_f32_e32 v9, v26, v8
	global_store_dword v[6:7], v9, off offset:32
	global_load_dword v8, v[2:3], off offset:36
	s_nop 0
	global_load_dword v9, v[4:5], off offset:36
	s_waitcnt vmcnt(0)
	v_fmac_f32_e32 v9, v26, v8
	global_store_dword v[6:7], v9, off offset:36
	global_load_dword v8, v[2:3], off offset:40
	s_nop 0
	global_load_dword v9, v[4:5], off offset:40
	s_waitcnt vmcnt(0)
	v_fmac_f32_e32 v9, v26, v8
	global_store_dword v[6:7], v9, off offset:40
	global_load_dword v8, v[2:3], off offset:44
	s_nop 0
	global_load_dword v9, v[4:5], off offset:44
	s_waitcnt vmcnt(0)
	v_fmac_f32_e32 v9, v26, v8
	global_store_dword v[6:7], v9, off offset:44
	global_load_dword v8, v[2:3], off offset:48
	s_nop 0
	global_load_dword v9, v[4:5], off offset:48
	s_waitcnt vmcnt(0)
	v_fmac_f32_e32 v9, v26, v8
	global_store_dword v[6:7], v9, off offset:48
	global_load_dword v8, v[2:3], off offset:52
	s_nop 0
	global_load_dword v9, v[4:5], off offset:52
	s_waitcnt vmcnt(0)
	v_fmac_f32_e32 v9, v26, v8
	global_store_dword v[6:7], v9, off offset:52
	global_load_dword v8, v[2:3], off offset:56
	s_nop 0
	global_load_dword v9, v[4:5], off offset:56
	s_waitcnt vmcnt(0)
	v_fmac_f32_e32 v9, v26, v8
	global_store_dword v[6:7], v9, off offset:56
	global_load_dword v2, v[2:3], off offset:60
	s_nop 0
	global_load_dword v3, v[4:5], off offset:60
	s_waitcnt vmcnt(0)
	v_fmac_f32_e32 v3, v26, v2
	global_store_dword v[6:7], v3, off offset:60

.LBB0_982:
	s_not_b32 s0, s40
	s_add_i32 s0, s41, s0
	s_cmp_lt_i32 s0, 1
	s_movk_i32 s0, 0x4000
	s_cbranch_scc1 .LBB0_985
	s_or_b32 s8, s12, 1
	s_ashr_i32 s9, s8, 31
	s_lshl_b64 s[8:9], s[8:9], 18
	v_lshl_add_u64 v[22:23], v[82:83], 0, s[8:9]
	v_mov_b32_e32 v19, v18
	s_add_i32 s8, s41, -1
	s_add_i32 s70, s40, 1
	s_mov_b32 s72, s8
	s_mov_b32 s75, 0
	s_max_i32 s74, s72, s70
	s_lshl_b32 s74, s74, 14
	s_add_i32 s72, s72, -1
	v_lshl_add_u64 v[240:241], v[22:23], 0, s[74:75]
	global_load_dwordx4 v[108:111], v[240:241], off
	global_load_dwordx4 v[112:115], v[240:241], off offset:16
	global_load_dwordx4 v[116:119], v[240:241], off offset:32
	global_load_dwordx4 v[120:123], v[240:241], off offset:48
	s_max_i32 s74, s72, s70
	s_lshl_b32 s74, s74, 14
	s_add_i32 s72, s72, -1
	v_lshl_add_u64 v[240:241], v[22:23], 0, s[74:75]
	global_load_dwordx4 v[124:127], v[240:241], off
	global_load_dwordx4 v[128:131], v[240:241], off offset:16
	global_load_dwordx4 v[132:135], v[240:241], off offset:32
	global_load_dwordx4 v[136:139], v[240:241], off offset:48
	s_max_i32 s74, s72, s70
	s_lshl_b32 s74, s74, 14
	s_add_i32 s72, s72, -1
	v_lshl_add_u64 v[240:241], v[22:23], 0, s[74:75]
	global_load_dwordx4 v[160:163], v[240:241], off
	global_load_dwordx4 v[164:167], v[240:241], off offset:16
	global_load_dwordx4 v[168:171], v[240:241], off offset:32
	global_load_dwordx4 v[172:175], v[240:241], off offset:48
.LBB0_984:
	s_max_i32 s74, s72, s70
	s_lshl_b32 s74, s74, 14
	s_add_i32 s72, s72, -1
	v_lshl_add_u64 v[240:241], v[22:23], 0, s[74:75]
	global_load_dwordx4 v[216:219], v[240:241], off
	global_load_dwordx4 v[220:223], v[240:241], off offset:16
	global_load_dwordx4 v[224:227], v[240:241], off offset:32
	global_load_dwordx4 v[228:231], v[240:241], off offset:48
	s_waitcnt vmcnt(12)
	v_pk_fma_f32 v[2:3], v[18:19], v[2:3], v[108:109]
	v_pk_fma_f32 v[4:5], v[18:19], v[4:5], v[110:111]
	v_pk_fma_f32 v[6:7], v[18:19], v[6:7], v[112:113]
	v_pk_fma_f32 v[8:9], v[18:19], v[8:9], v[114:115]
	v_pk_fma_f32 v[10:11], v[18:19], v[10:11], v[116:117]
	v_pk_fma_f32 v[12:13], v[18:19], v[12:13], v[118:119]
	v_pk_fma_f32 v[14:15], v[18:19], v[14:15], v[120:121]
	v_pk_fma_f32 v[16:17], v[18:19], v[16:17], v[122:123]
	s_add_i32 s8, s8, -1
	s_cmp_lg_u32 s40, s8
	s_cbranch_scc0 .Lp2c_bdone
	s_max_i32 s74, s72, s70
	s_lshl_b32 s74, s74, 14
	s_add_i32 s72, s72, -1
	v_lshl_add_u64 v[240:241], v[22:23], 0, s[74:75]
	global_load_dwordx4 v[108:111], v[240:241], off
	global_load_dwordx4 v[112:115], v[240:241], off offset:16
	global_load_dwordx4 v[116:119], v[240:241], off offset:32
	global_load_dwordx4 v[120:123], v[240:241], off offset:48
	s_waitcnt vmcnt(12)
	v_pk_fma_f32 v[2:3], v[18:19], v[2:3], v[124:125]
	v_pk_fma_f32 v[4:5], v[18:19], v[4:5], v[126:127]
	v_pk_fma_f32 v[6:7], v[18:19], v[6:7], v[128:129]
	v_pk_fma_f32 v[8:9], v[18:19], v[8:9], v[130:131]
	v_pk_fma_f32 v[10:11], v[18:19], v[10:11], v[132:133]
	v_pk_fma_f32 v[12:13], v[18:19], v[12:13], v[134:135]
	v_pk_fma_f32 v[14:15], v[18:19], v[14:15], v[136:137]
	v_pk_fma_f32 v[16:17], v[18:19], v[16:17], v[138:139]
	s_add_i32 s8, s8, -1
	s_cmp_lg_u32 s40, s8
	s_cbranch_scc0 .Lp2c_bdone
	s_max_i32 s74, s72, s70
	s_lshl_b32 s74, s74, 14
	s_add_i32 s72, s72, -1
	v_lshl_add_u64 v[240:241], v[22:23], 0, s[74:75]
	global_load_dwordx4 v[124:127], v[240:241], off
	global_load_dwordx4 v[128:131], v[240:241], off offset:16
	global_load_dwordx4 v[132:135], v[240:241], off offset:32
	global_load_dwordx4 v[136:139], v[240:241], off offset:48
	s_waitcnt vmcnt(12)
	v_pk_fma_f32 v[2:3], v[18:19], v[2:3], v[160:161]
	v_pk_fma_f32 v[4:5], v[18:19], v[4:5], v[162:163]
	v_pk_fma_f32 v[6:7], v[18:19], v[6:7], v[164:165]
	v_pk_fma_f32 v[8:9], v[18:19], v[8:9], v[166:167]
	v_pk_fma_f32 v[10:11], v[18:19], v[10:11], v[168:169]
	v_pk_fma_f32 v[12:13], v[18:19], v[12:13], v[170:171]
	v_pk_fma_f32 v[14:15], v[18:19], v[14:15], v[172:173]
	v_pk_fma_f32 v[16:17], v[18:19], v[16:17], v[174:175]
	s_add_i32 s8, s8, -1
	s_cmp_lg_u32 s40, s8
	s_cbranch_scc0 .Lp2c_bdone
	s_max_i32 s74, s72, s70
	s_lshl_b32 s74, s74, 14
	s_add_i32 s72, s72, -1
	v_lshl_add_u64 v[240:241], v[22:23], 0, s[74:75]
	global_load_dwordx4 v[160:163], v[240:241], off
	global_load_dwordx4 v[164:167], v[240:241], off offset:16
	global_load_dwordx4 v[168:171], v[240:241], off offset:32
	global_load_dwordx4 v[172:175], v[240:241], off offset:48
	s_waitcnt vmcnt(12)
	v_pk_fma_f32 v[2:3], v[18:19], v[2:3], v[216:217]
	v_pk_fma_f32 v[4:5], v[18:19], v[4:5], v[218:219]
	v_pk_fma_f32 v[6:7], v[18:19], v[6:7], v[220:221]
	v_pk_fma_f32 v[8:9], v[18:19], v[8:9], v[222:223]
	v_pk_fma_f32 v[10:11], v[18:19], v[10:11], v[224:225]
	v_pk_fma_f32 v[12:13], v[18:19], v[12:13], v[226:227]
	v_pk_fma_f32 v[14:15], v[18:19], v[14:15], v[228:229]
	v_pk_fma_f32 v[16:17], v[18:19], v[16:17], v[230:231]
	s_add_i32 s8, s8, -1
	s_cmp_lg_u32 s40, s8
	s_cbranch_scc1 .LBB0_984
.Lp2c_bdone:
.LBB0_985:
	s_waitcnt vmcnt(3)
	v_cvt_pk_bf16_f32 v2, v2, s0
	ds_write_b16 v105, v2 offset:45056
	v_cvt_pk_bf16_f32 v2, v3, s0
	ds_write_b16 v105, v2 offset:45200
	v_cvt_pk_bf16_f32 v2, v4, s0
	ds_write_b16 v105, v2 offset:45344
	v_cvt_pk_bf16_f32 v2, v5, s0
	ds_write_b16 v105, v2 offset:45488
	s_waitcnt vmcnt(2)
	v_cvt_pk_bf16_f32 v2, v6, s0
	ds_write_b16 v105, v2 offset:45632
	v_cvt_pk_bf16_f32 v2, v7, s0
	ds_write_b16 v105, v2 offset:45776
	v_cvt_pk_bf16_f32 v2, v8, s0
	ds_write_b16 v105, v2 offset:45920
	v_cvt_pk_bf16_f32 v2, v9, s0
	ds_write_b16 v105, v2 offset:46064
	s_waitcnt vmcnt(1)
	v_cvt_pk_bf16_f32 v2, v10, s0
	ds_write_b16 v105, v2 offset:46208
	v_cvt_pk_bf16_f32 v2, v11, s0
	ds_write_b16 v105, v2 offset:46352
	v_cvt_pk_bf16_f32 v2, v12, s0
	ds_write_b16 v105, v2 offset:46496
	v_cvt_pk_bf16_f32 v2, v13, s0
	ds_write_b16 v105, v2 offset:46640
	s_waitcnt vmcnt(0)
	v_cvt_pk_bf16_f32 v2, v14, s0
	ds_write_b16 v105, v2 offset:46784
	v_cvt_pk_bf16_f32 v2, v15, s0
	ds_write_b16 v105, v2 offset:46928
	v_cvt_pk_bf16_f32 v2, v16, s0
	ds_write_b16 v105, v2 offset:47072
	v_cvt_pk_bf16_f32 v2, v17, s0
	s_andn2_b64 vcc, exec, s[14:15]
	ds_write_b16 v105, v2 offset:47216
	s_cbranch_vccnz .LBB0_987
	s_or_b32 s8, s12, 1
	s_ashr_i32 s9, s8, 31
	v_readlane_b32 s44, v247, 49
	s_lshl_b64 s[8:9], s[8:9], 18
	v_readlane_b32 s54, v247, 59
	v_lshl_add_u64 v[2:3], v[82:83], 0, s[8:9]
	v_readlane_b32 s55, v247, 60
	s_add_u32 s8, s54, s8
	s_addc_u32 s9, s55, s9
	v_lshl_add_u64 v[4:5], v[68:69], 2, s[8:9]
	v_mov_b32_e32 v25, v1
	v_lshl_add_u64 v[4:5], v[4:5], 0, v[24:25]
	v_add_co_u32_e32 v6, vcc, s0, v4
	s_or_b32 s6, s6, 1
	s_nop 0
	v_addc_co_u32_e32 v7, vcc, 0, v5, vcc
	global_load_dword v8, v[6:7], off
	global_load_dword v9, v[2:3], off
	s_ashr_i32 s7, s6, 31
	s_lshl_b64 s[6:7], s[6:7], 16
	s_mov_b64 s[8:9], 0x4000
	v_lshl_add_u64 v[6:7], v[20:21], 0, s[6:7]
	v_lshl_add_u64 v[4:5], v[4:5], 0, s[8:9]
	v_readlane_b32 s45, v247, 50
	v_readlane_b32 s46, v247, 51
	v_readlane_b32 s47, v247, 52
	v_readlane_b32 s48, v247, 53
	v_readlane_b32 s49, v247, 54
	v_readlane_b32 s50, v247, 55
	v_readlane_b32 s51, v247, 56
	v_readlane_b32 s52, v247, 57
	v_readlane_b32 s53, v247, 58
	v_readlane_b32 s56, v247, 61
	v_readlane_b32 s57, v247, 62
	v_readlane_b32 s58, v247, 63
	v_readlane_b32 s59, v246, 0
	s_waitcnt vmcnt(0)
	v_fmac_f32_e32 v9, v18, v8
	global_store_dword v[6:7], v9, off
	global_load_dword v8, v[4:5], off offset:4
	s_nop 0
	global_load_dword v9, v[2:3], off offset:4
	s_waitcnt vmcnt(0)
	v_fmac_f32_e32 v9, v18, v8
	global_store_dword v[6:7], v9, off offset:4
	global_load_dword v8, v[4:5], off offset:8
	s_nop 0
	global_load_dword v9, v[2:3], off offset:8
	s_waitcnt vmcnt(0)
	v_fmac_f32_e32 v9, v18, v8
	global_store_dword v[6:7], v9, off offset:8
	global_load_dword v8, v[4:5], off offset:12
	s_nop 0
	global_load_dword v9, v[2:3], off offset:12
	s_waitcnt vmcnt(0)
	v_fmac_f32_e32 v9, v18, v8
	global_store_dword v[6:7], v9, off offset:12
	global_load_dword v8, v[4:5], off offset:16
	s_nop 0
	global_load_dword v9, v[2:3], off offset:16
	s_waitcnt vmcnt(0)
	v_fmac_f32_e32 v9, v18, v8
	global_store_dword v[6:7], v9, off offset:16
	global_load_dword v8, v[4:5], off offset:20
	s_nop 0
	global_load_dword v9, v[2:3], off offset:20
	s_waitcnt vmcnt(0)
	v_fmac_f32_e32 v9, v18, v8
	global_store_dword v[6:7], v9, off offset:20
	global_load_dword v8, v[4:5], off offset:24
	s_nop 0
	global_load_dword v9, v[2:3], off offset:24
	s_waitcnt vmcnt(0)
	v_fmac_f32_e32 v9, v18, v8
	global_store_dword v[6:7], v9, off offset:24
	global_load_dword v8, v[4:5], off offset:28
	s_nop 0
	global_load_dword v9, v[2:3], off offset:28
	s_waitcnt vmcnt(0)
	v_fmac_f32_e32 v9, v18, v8
	global_store_dword v[6:7], v9, off offset:28
	global_load_dword v8, v[4:5], off offset:32
	s_nop 0
	global_load_dword v9, v[2:3], off offset:32
	s_waitcnt vmcnt(0)
	v_fmac_f32_e32 v9, v18, v8
	global_store_dword v[6:7], v9, off offset:32
	global_load_dword v8, v[4:5], off offset:36
	s_nop 0
	global_load_dword v9, v[2:3], off offset:36
	s_waitcnt vmcnt(0)
	v_fmac_f32_e32 v9, v18, v8
	global_store_dword v[6:7], v9, off offset:36
	global_load_dword v8, v[4:5], off offset:40
	s_nop 0
	global_load_dword v9, v[2:3], off offset:40
	s_waitcnt vmcnt(0)
	v_fmac_f32_e32 v9, v18, v8
	global_store_dword v[6:7], v9, off offset:40
	global_load_dword v8, v[4:5], off offset:44
	s_nop 0
	global_load_dword v9, v[2:3], off offset:44
	s_waitcnt vmcnt(0)
	v_fmac_f32_e32 v9, v18, v8
	global_store_dword v[6:7], v9, off offset:44
	global_load_dword v8, v[4:5], off offset:48
	s_nop 0
	global_load_dword v9, v[2:3], off offset:48
	s_waitcnt vmcnt(0)
	v_fmac_f32_e32 v9, v18, v8
	global_store_dword v[6:7], v9, off offset:48
	global_load_dword v8, v[4:5], off offset:52
	s_nop 0
	global_load_dword v9, v[2:3], off offset:52
	s_waitcnt vmcnt(0)
	v_fmac_f32_e32 v9, v18, v8
	global_store_dword v[6:7], v9, off offset:52
	global_load_dword v8, v[4:5], off offset:56
	s_nop 0
	global_load_dword v9, v[2:3], off offset:56
	s_waitcnt vmcnt(0)
	v_fmac_f32_e32 v9, v18, v8
	global_store_dword v[6:7], v9, off offset:56
	global_load_dword v4, v[4:5], off offset:60
	s_nop 0
	global_load_dword v2, v[2:3], off offset:60
	s_waitcnt vmcnt(0)
	v_fmac_f32_e32 v2, v18, v4
	global_store_dword v[6:7], v2, off offset:60
